# P.V epilogue hx stores marked non-temporal (64-byte pieces after widening): they are next read two phases later, so they no longer displace the P tiles and V^T tiles in L2 during P.V
# baseline (speedup 1.0000x reference)
; __device__ __forceinline__ u32x2 pk4(f32x4 v) { u32x2 r; r.x = pk_bf16(v[0], v[1]); r.y = pk_bf16(v[2], v[3]); return r; }
; __device__ __forceinline__ f32x4 unpk4(u32x2 v) { return (f32x4){bf_lo(v.x), bf_hi(v.x), bf_lo(v.y), bf_hi(v.y)}; }
;     __device__ __forceinline__ void operator()(const f32x4 (&acc)[2][2][4][2], const Unit& u, int wr, int wc, int fr_in, int fq_in) const {
;     ...
;         const int w4 = wr * 4 + wc, lane = fq * 16 + fr;
; #pragma unroll
;         for (int ai = 0; ai < 2; ++ai) {
;             u32x2 z[4][2][2]; float rs[4];
; #pragma unroll
;             for (int m = 0; m < 4; ++m) {
;                 rs[m] = RSUM[(u.pm * 256 + ai * 128 + wr * 64 + m * 16 + fr) * 4 + u.pn];
; #pragma unroll
;                 for (int bj = 0; bj < 2; ++bj)
; #pragma unroll
;                     for (int n = 0; n < 2; ++n) z[m][bj][n] = __builtin_nontemporal_load((const u32x2*)SZXN + native_slot(u.pm, u.pn, w4, ai, m, bj, n, lane));
;             }
; #pragma unroll
;             for (int m = 0; m < 4; ++m) {
;                 const int row = u.pm * 256 + ai * 128 + wr * 64 + m * 16 + fr; const float inv = __builtin_amdgcn_rcpf(rs[m]);
; #pragma unroll
;                 for (int bj = 0; bj < 2; ++bj)
; #pragma unroll
;                     for (int n = 0; n < 2; ++n)
;                         *(u32x2*)(HX + (size_t)row * 1024 + u.pn * 256 + bj * 128 + wc * 32 + n * 16 + fq * 4) = pk4(unpk4(z[m][bj][n]) * (acc[ai][bj][m][n] * inv));
.LBB0_468:
	v_mbcnt_lo_u32_b32 v242, -1, 0
	v_mbcnt_hi_u32_b32 v242, -1, v242
	v_lshrrev_b32_e32 v242, 1, v242
	v_and_b32_e32 v242, 24, v242
	v_mov_b32_e32 v243, 0
	s_lshl_b32 s29, s28, 2
	s_add_i32 s60, s29, s78
	s_lshl_b32 s29, s28, 10
	v_mov_b32_e32 v142, v152
	v_mov_b32_e32 v143, v153
	s_add_i32 s29, s29, s43
	s_ashr_i32 s61, s60, 31
	v_lshl_add_u32 v136, v143, 4, v142
	v_lshl_add_u32 v159, v142, 2, s29
	v_ashrrev_i32_e32 v137, 31, v136
	v_add_u32_e32 v138, s78, v159
	v_lshl_add_u64 v[136:137], v[136:137], 3, s[92:93]
	v_ashrrev_i32_e32 v139, 31, v138
	s_lshl_b64 s[60:61], s[60:61], 17
	v_lshl_add_u64 v[138:139], v[138:139], 2, s[44:45]
	v_lshl_add_u64 v[136:137], v[136:137], 0, s[60:61]
	v_lshl_add_u64 v[140:141], v[136:137], 0, s[30:31]
	global_load_dword v188, v[138:139], off
	global_load_dwordx2 v[160:161], v[140:141], off nt
	global_load_dwordx2 v[162:163], v[140:141], off offset:512 nt
	global_load_dwordx2 v[164:165], v[140:141], off offset:1024 nt
	s_lshl_b32 s29, s28, 8
	s_add_i32 s53, s78, 64
	s_add_i32 s62, s29, s40
	v_add_u32_e32 v138, s62, v142
	v_add_u32_e32 v142, s53, v159
	global_load_dwordx2 v[166:167], v[140:141], off offset:1536 nt
	global_load_dwordx2 v[168:169], v[140:141], off offset:2048 nt
	v_lshlrev_b32_e32 v136, 2, v143
	v_ashrrev_i32_e32 v143, 31, v142
	v_lshl_add_u64 v[142:143], v[142:143], 2, s[44:45]
	global_load_dword v192, v[142:143], off
	global_load_dwordx2 v[170:171], v[140:141], off offset:2560 nt
	global_load_dwordx2 v[172:173], v[140:141], off offset:3072 nt
	s_add_i32 s60, s78, 0x80
	s_add_i32 s61, s78, 0xc0
	s_lshl_b32 s28, s78, 8
	v_ashrrev_i32_e32 v139, 31, v138
	s_ashr_i32 s29, s28, 31
	v_add_u32_e32 v144, s60, v159
	v_add_u32_e32 v146, s61, v159
	v_lshlrev_b64 v[142:143], 11, v[138:139]
	v_add_co_u32_e32 v174, vcc, s67, v140
	s_lshl_b64 s[28:29], s[28:29], 1
	v_ashrrev_i32_e32 v145, 31, v144
	v_ashrrev_i32_e32 v147, 31, v146
	v_lshl_add_u64 v[142:143], s[24:25], 0, v[142:143]
	v_addc_co_u32_e32 v175, vcc, 0, v141, vcc
	v_lshl_add_u64 v[144:145], v[144:145], 2, s[44:45]
	v_lshl_add_u64 v[146:147], v[146:147], 2, s[44:45]
	v_lshl_add_u64 v[148:149], v[142:143], 0, s[28:29]
	v_add_co_u32_e32 v142, vcc, s35, v140
	v_lshl_add_u64 v[176:177], v[148:149], 0, s[6:7]
	s_nop 0
	v_addc_co_u32_e32 v143, vcc, 0, v141, vcc
	global_load_dword v139, v[144:145], off
	global_load_dwordx2 v[178:179], v[174:175], off offset:512 nt
	global_load_dwordx2 v[180:181], v[140:141], off offset:3584 nt
	global_load_dwordx2 v[182:183], v[174:175], off offset:1024 nt
	global_load_dwordx2 v[184:185], v[174:175], off offset:1536 nt
	global_load_dwordx2 v[150:151], v[174:175], off offset:2048 nt
	global_load_dwordx2 v[148:149], v[174:175], off offset:2560 nt
	global_load_dwordx2 v[186:187], v[142:143], off offset:-4096 nt
	global_load_dword v193, v[146:147], off
	s_nop 0
	global_load_dwordx2 v[146:147], v[174:175], off offset:3072 nt
	global_load_dwordx2 v[144:145], v[174:175], off offset:3584 nt
	v_ashrrev_i32_e32 v137, 31, v136
	v_lshlrev_b64 v[136:137], 1, v[136:137]
	v_lshl_add_u64 v[174:175], v[176:177], 0, v[136:137]
	s_waitcnt vmcnt(0)
	v_rcp_f32_e32 v176, v188
	v_lshlrev_b32_e32 v188, 16, v160
	v_lshlrev_b32_e32 v190, 16, v162
	v_and_b32_e32 v191, 0xffff0000, v162
	v_lshlrev_b32_e32 v162, 16, v163
	v_and_b32_e32 v163, 0xffff0000, v163
	v_pk_mul_f32 v[120:121], v[120:121], v[176:177] op_sel_hi:[1,0]
	v_pk_mul_f32 v[122:123], v[122:123], v[176:177] op_sel_hi:[1,0]
	v_pk_mul_f32 v[120:121], v[120:121], v[190:191]
	v_pk_mul_f32 v[122:123], v[122:123], v[162:163]
	v_cvt_pk_bf16_f32 v120, v120, v121
	v_cvt_pk_bf16_f32 v121, v122, v123
	v_mov_b32_e32 v198, v120
	v_mov_b32_e32 v199, v121
	v_lshlrev_b32_e32 v120, 16, v164
	v_and_b32_e32 v121, 0xffff0000, v164
	v_lshlrev_b32_e32 v122, 16, v165
	v_and_b32_e32 v123, 0xffff0000, v165
	v_pk_mul_f32 v[116:117], v[116:117], v[176:177] op_sel_hi:[1,0]
	v_pk_mul_f32 v[118:119], v[118:119], v[176:177] op_sel_hi:[1,0]
	v_pk_mul_f32 v[116:117], v[116:117], v[120:121]
	v_pk_mul_f32 v[118:119], v[118:119], v[122:123]
	v_cvt_pk_bf16_f32 v116, v116, v117
	v_cvt_pk_bf16_f32 v117, v118, v119
	v_mov_b32_e32 v200, v116
	v_mov_b32_e32 v201, v117
	v_lshlrev_b32_e32 v116, 16, v166
	v_and_b32_e32 v117, 0xffff0000, v166
	v_lshlrev_b32_e32 v118, 16, v167
	v_and_b32_e32 v119, 0xffff0000, v167
	v_pk_mul_f32 v[112:113], v[112:113], v[176:177] op_sel_hi:[1,0]
	v_pk_mul_f32 v[114:115], v[114:115], v[176:177] op_sel_hi:[1,0]
	v_pk_mul_f32 v[112:113], v[112:113], v[116:117]
	v_pk_mul_f32 v[114:115], v[114:115], v[118:119]
	v_cvt_pk_bf16_f32 v112, v112, v113
	v_cvt_pk_bf16_f32 v113, v114, v115
	v_rcp_f32_e32 v114, v192
	v_mov_b32_e32 v202, v112
	v_mov_b32_e32 v203, v113
	v_add_u32_e32 v112, 16, v138
	v_ashrrev_i32_e32 v113, 31, v112
	v_lshlrev_b32_e32 v116, 16, v168
	v_and_b32_e32 v117, 0xffff0000, v168
	v_lshlrev_b32_e32 v118, 16, v169
	v_and_b32_e32 v119, 0xffff0000, v169
	v_pk_mul_f32 v[108:109], v[108:109], v[114:115] op_sel_hi:[1,0]
	v_pk_mul_f32 v[110:111], v[110:111], v[114:115] op_sel_hi:[1,0]
	v_lshlrev_b64 v[112:113], 11, v[112:113]
	v_pk_mul_f32 v[110:111], v[110:111], v[118:119]
	v_pk_mul_f32 v[108:109], v[108:109], v[116:117]
	v_pk_mul_f32 v[104:105], v[104:105], v[114:115] op_sel_hi:[1,0]
	v_cvt_pk_bf16_f32 v108, v108, v109
	v_cvt_pk_bf16_f32 v109, v110, v111
	v_lshl_add_u64 v[110:111], s[24:25], 0, v[112:113]
	v_lshl_add_u64 v[110:111], v[110:111], 0, s[28:29]
	v_lshl_add_u64 v[110:111], v[110:111], 0, s[6:7]
	v_lshl_add_u64 v[110:111], v[110:111], 0, v[136:137]
	v_mov_b32_e32 v204, v108
	v_mov_b32_e32 v205, v109
	v_lshlrev_b32_e32 v108, 16, v170
	v_and_b32_e32 v109, 0xffff0000, v170
; __device__ __forceinline__ u32x2 pk4(f32x4 v) { u32x2 r; r.x = pk_bf16(v[0], v[1]); r.y = pk_bf16(v[2], v[3]); return r; }
; __device__ __forceinline__ f32x4 unpk4(u32x2 v) { return (f32x4){bf_lo(v.x), bf_hi(v.x), bf_lo(v.y), bf_hi(v.y)}; }
;     __device__ __forceinline__ void operator()(const f32x4 (&acc)[2][2][4][2], const Unit& u, int wr, int wc, int fr_in, int fq_in) const {
;     ...
; #pragma unroll
;             for (int m = 0; m < 4; ++m) {
;                 const int row = u.pm * 256 + ai * 128 + wr * 64 + m * 16 + fr; const float inv = __builtin_amdgcn_rcpf(rs[m]);
; #pragma unroll
;                 for (int bj = 0; bj < 2; ++bj)
; #pragma unroll
;                     for (int n = 0; n < 2; ++n)
;                         *(u32x2*)(HX + (size_t)row * 1024 + u.pn * 256 + bj * 128 + wc * 32 + n * 16 + fq * 4) = pk4(unpk4(z[m][bj][n]) * (acc[ai][bj][m][n] * inv));
;             }
	v_lshlrev_b32_e32 v112, 16, v171
	v_and_b32_e32 v113, 0xffff0000, v171
	v_pk_mul_f32 v[106:107], v[106:107], v[114:115] op_sel_hi:[1,0]
	v_pk_mul_f32 v[104:105], v[104:105], v[108:109]
	v_pk_mul_f32 v[106:107], v[106:107], v[112:113]
	v_cvt_pk_bf16_f32 v104, v104, v105
	v_cvt_pk_bf16_f32 v105, v106, v107
	v_mov_b32_e32 v206, v104
	v_mov_b32_e32 v207, v105
	v_lshlrev_b32_e32 v104, 16, v172
	v_and_b32_e32 v105, 0xffff0000, v172
	v_lshlrev_b32_e32 v106, 16, v173
	v_and_b32_e32 v107, 0xffff0000, v173
	v_pk_mul_f32 v[100:101], v[100:101], v[114:115] op_sel_hi:[1,0]
	v_pk_mul_f32 v[102:103], v[102:103], v[114:115] op_sel_hi:[1,0]
	v_pk_mul_f32 v[100:101], v[100:101], v[104:105]
	v_pk_mul_f32 v[102:103], v[102:103], v[106:107]
	v_cvt_pk_bf16_f32 v100, v100, v101
	v_cvt_pk_bf16_f32 v101, v102, v103
	v_mov_b32_e32 v208, v100
	v_mov_b32_e32 v209, v101
	v_lshlrev_b32_e32 v100, 16, v180
	v_and_b32_e32 v101, 0xffff0000, v180
	v_lshlrev_b32_e32 v102, 16, v181
	v_and_b32_e32 v103, 0xffff0000, v181
	v_pk_mul_f32 v[96:97], v[96:97], v[114:115] op_sel_hi:[1,0]
	v_pk_mul_f32 v[98:99], v[98:99], v[114:115] op_sel_hi:[1,0]
	v_pk_mul_f32 v[96:97], v[96:97], v[100:101]
	v_pk_mul_f32 v[98:99], v[98:99], v[102:103]
	v_cvt_pk_bf16_f32 v96, v96, v97
	v_cvt_pk_bf16_f32 v97, v98, v99
	v_rcp_f32_e32 v98, v139
	v_mov_b32_e32 v210, v96
	v_mov_b32_e32 v211, v97
	s_nop 1
	v_permlane32_swap_b32_e32 v204, v206
	v_permlane32_swap_b32_e32 v205, v207
	v_permlane32_swap_b32_e32 v208, v210
	v_permlane32_swap_b32_e32 v209, v211
	v_permlane16_swap_b32_e32 v204, v206
	v_permlane16_swap_b32_e32 v205, v207
	v_permlane16_swap_b32_e32 v208, v210
	v_permlane16_swap_b32_e32 v209, v211
	v_lshl_add_u64 v[240:241], v[110:111], 0, v[242:243]
	global_store_dwordx4 v[240:241], v[204:207], off nt
	global_store_dwordx4 v[240:241], v[208:211], off offset:256 nt
	v_add_u32_e32 v96, 32, v138
	v_ashrrev_i32_e32 v97, 31, v96
	v_lshlrev_b32_e32 v100, 16, v186
	v_and_b32_e32 v101, 0xffff0000, v186
	v_lshlrev_b32_e32 v102, 16, v187
	v_and_b32_e32 v103, 0xffff0000, v187
	v_pk_mul_f32 v[92:93], v[92:93], v[98:99] op_sel_hi:[1,0]
	v_pk_mul_f32 v[94:95], v[94:95], v[98:99] op_sel_hi:[1,0]
	v_lshlrev_b64 v[96:97], 11, v[96:97]
	v_pk_mul_f32 v[94:95], v[94:95], v[102:103]
	v_pk_mul_f32 v[92:93], v[92:93], v[100:101]
	v_pk_mul_f32 v[88:89], v[88:89], v[98:99] op_sel_hi:[1,0]
	v_cvt_pk_bf16_f32 v92, v92, v93
	v_cvt_pk_bf16_f32 v93, v94, v95
	v_lshl_add_u64 v[94:95], s[24:25], 0, v[96:97]
	v_lshl_add_u64 v[94:95], v[94:95], 0, s[28:29]
	v_lshl_add_u64 v[94:95], v[94:95], 0, s[6:7]
	v_lshl_add_u64 v[94:95], v[94:95], 0, v[136:137]
	v_mov_b32_e32 v212, v92
	v_mov_b32_e32 v213, v93
	v_lshlrev_b32_e32 v92, 16, v178
	v_and_b32_e32 v93, 0xffff0000, v178
	v_lshlrev_b32_e32 v96, 16, v179
	v_and_b32_e32 v97, 0xffff0000, v179
	v_pk_mul_f32 v[90:91], v[90:91], v[98:99] op_sel_hi:[1,0]
	v_pk_mul_f32 v[88:89], v[88:89], v[92:93]
	v_pk_mul_f32 v[90:91], v[90:91], v[96:97]
	v_cvt_pk_bf16_f32 v88, v88, v89
	v_cvt_pk_bf16_f32 v89, v90, v91
	v_mov_b32_e32 v214, v88
	v_mov_b32_e32 v215, v89
	v_lshlrev_b32_e32 v88, 16, v182
	v_and_b32_e32 v89, 0xffff0000, v182
	v_lshlrev_b32_e32 v90, 16, v183
	v_and_b32_e32 v91, 0xffff0000, v183
	v_pk_mul_f32 v[84:85], v[84:85], v[98:99] op_sel_hi:[1,0]
	v_pk_mul_f32 v[86:87], v[86:87], v[98:99] op_sel_hi:[1,0]
	v_pk_mul_f32 v[84:85], v[84:85], v[88:89]
	v_pk_mul_f32 v[86:87], v[86:87], v[90:91]
	v_cvt_pk_bf16_f32 v84, v84, v85
	v_cvt_pk_bf16_f32 v85, v86, v87
	v_mov_b32_e32 v216, v84
	v_mov_b32_e32 v217, v85
	v_lshlrev_b32_e32 v84, 16, v184
	v_and_b32_e32 v85, 0xffff0000, v184
	v_lshlrev_b32_e32 v86, 16, v185
	v_and_b32_e32 v87, 0xffff0000, v185
	v_pk_mul_f32 v[80:81], v[80:81], v[98:99] op_sel_hi:[1,0]
	v_pk_mul_f32 v[82:83], v[82:83], v[98:99] op_sel_hi:[1,0]
	v_pk_mul_f32 v[80:81], v[80:81], v[84:85]
	v_pk_mul_f32 v[82:83], v[82:83], v[86:87]
	v_cvt_pk_bf16_f32 v80, v80, v81
	v_cvt_pk_bf16_f32 v81, v82, v83
	v_rcp_f32_e32 v82, v193
	v_mov_b32_e32 v218, v80
	v_mov_b32_e32 v219, v81
	s_nop 1
	v_permlane32_swap_b32_e32 v212, v214
	v_permlane32_swap_b32_e32 v213, v215
	v_permlane32_swap_b32_e32 v216, v218
	v_permlane32_swap_b32_e32 v217, v219
	v_permlane16_swap_b32_e32 v212, v214
	v_permlane16_swap_b32_e32 v213, v215
	v_permlane16_swap_b32_e32 v216, v218
	v_permlane16_swap_b32_e32 v217, v219
	v_lshl_add_u64 v[240:241], v[94:95], 0, v[242:243]
	global_store_dwordx4 v[240:241], v[212:215], off nt
	global_store_dwordx4 v[240:241], v[216:219], off offset:256 nt
	v_add_u32_e32 v80, 48, v138
	v_ashrrev_i32_e32 v81, 31, v80
	v_lshlrev_b32_e32 v84, 16, v150
	v_and_b32_e32 v85, 0xffff0000, v150
	v_lshlrev_b32_e32 v86, 16, v151
	v_and_b32_e32 v87, 0xffff0000, v151
	v_pk_mul_f32 v[76:77], v[76:77], v[82:83] op_sel_hi:[1,0]
	v_pk_mul_f32 v[78:79], v[78:79], v[82:83] op_sel_hi:[1,0]
	v_lshlrev_b64 v[80:81], 11, v[80:81]
	v_pk_mul_f32 v[78:79], v[78:79], v[86:87]
	v_pk_mul_f32 v[76:77], v[76:77], v[84:85]
	v_pk_mul_f32 v[72:73], v[72:73], v[82:83] op_sel_hi:[1,0]
	v_cvt_pk_bf16_f32 v76, v76, v77
	v_cvt_pk_bf16_f32 v77, v78, v79
	v_lshl_add_u64 v[78:79], s[24:25], 0, v[80:81]
	v_lshl_add_u64 v[78:79], v[78:79], 0, s[28:29]
	v_lshl_add_u64 v[78:79], v[78:79], 0, s[6:7]
	v_lshl_add_u64 v[78:79], v[78:79], 0, v[136:137]
	v_mov_b32_e32 v224, v76
	v_mov_b32_e32 v225, v77
	v_lshlrev_b32_e32 v76, 16, v148
	v_and_b32_e32 v77, 0xffff0000, v148
	v_lshlrev_b32_e32 v80, 16, v149
	v_and_b32_e32 v81, 0xffff0000, v149
	v_pk_mul_f32 v[74:75], v[74:75], v[82:83] op_sel_hi:[1,0]
	v_pk_mul_f32 v[72:73], v[72:73], v[76:77]
	v_pk_mul_f32 v[74:75], v[74:75], v[80:81]
	v_cvt_pk_bf16_f32 v72, v72, v73
	v_cvt_pk_bf16_f32 v73, v74, v75
; __device__ __forceinline__ u32x2 pk4(f32x4 v) { u32x2 r; r.x = pk_bf16(v[0], v[1]); r.y = pk_bf16(v[2], v[3]); return r; }
; __device__ __forceinline__ f32x4 unpk4(u32x2 v) { return (f32x4){bf_lo(v.x), bf_hi(v.x), bf_lo(v.y), bf_hi(v.y)}; }
;     __device__ __forceinline__ void operator()(const f32x4 (&acc)[2][2][4][2], const Unit& u, int wr, int wc, int fr_in, int fq_in) const {
;     ...
;             for (int m = 0; m < 4; ++m) {
;                 rs[m] = RSUM[(u.pm * 256 + ai * 128 + wr * 64 + m * 16 + fr) * 4 + u.pn];
; #pragma unroll
;                 for (int bj = 0; bj < 2; ++bj)
; #pragma unroll
;                     for (int n = 0; n < 2; ++n) z[m][bj][n] = __builtin_nontemporal_load((const u32x2*)SZXN + native_slot(u.pm, u.pn, w4, ai, m, bj, n, lane));
;             }
; #pragma unroll
;             for (int m = 0; m < 4; ++m) {
;                 const int row = u.pm * 256 + ai * 128 + wr * 64 + m * 16 + fr; const float inv = __builtin_amdgcn_rcpf(rs[m]);
; #pragma unroll
;                 for (int bj = 0; bj < 2; ++bj)
; #pragma unroll
;                     for (int n = 0; n < 2; ++n)
;                         *(u32x2*)(HX + (size_t)row * 1024 + u.pn * 256 + bj * 128 + wc * 32 + n * 16 + fq * 4) = pk4(unpk4(z[m][bj][n]) * (acc[ai][bj][m][n] * inv));
	v_mov_b32_e32 v226, v72
	v_mov_b32_e32 v227, v73
	v_lshlrev_b32_e32 v72, 16, v146
	v_and_b32_e32 v73, 0xffff0000, v146
	v_lshlrev_b32_e32 v74, 16, v147
	v_and_b32_e32 v75, 0xffff0000, v147
	v_pk_mul_f32 v[68:69], v[68:69], v[82:83] op_sel_hi:[1,0]
	v_pk_mul_f32 v[70:71], v[70:71], v[82:83] op_sel_hi:[1,0]
	v_pk_mul_f32 v[68:69], v[68:69], v[72:73]
	v_pk_mul_f32 v[70:71], v[70:71], v[74:75]
	v_cvt_pk_bf16_f32 v68, v68, v69
	v_cvt_pk_bf16_f32 v69, v70, v71
	v_mov_b32_e32 v228, v68
	v_mov_b32_e32 v229, v69
	v_lshlrev_b32_e32 v68, 16, v144
	v_and_b32_e32 v69, 0xffff0000, v144
	v_lshlrev_b32_e32 v70, 16, v145
	v_and_b32_e32 v71, 0xffff0000, v145
	v_pk_mul_f32 v[64:65], v[64:65], v[82:83] op_sel_hi:[1,0]
	v_pk_mul_f32 v[66:67], v[66:67], v[82:83] op_sel_hi:[1,0]
	v_pk_mul_f32 v[64:65], v[64:65], v[68:69]
	v_pk_mul_f32 v[66:67], v[66:67], v[70:71]
	v_and_b32_e32 v189, 0xffff0000, v160
	v_lshlrev_b32_e32 v160, 16, v161
	v_and_b32_e32 v161, 0xffff0000, v161
	v_pk_mul_f32 v[124:125], v[124:125], v[176:177] op_sel_hi:[1,0]
	v_pk_mul_f32 v[126:127], v[126:127], v[176:177] op_sel_hi:[1,0]
	v_cvt_pk_bf16_f32 v64, v64, v65
	v_cvt_pk_bf16_f32 v65, v66, v67
	v_add_u32_e32 v66, 0x200, v159
	v_pk_mul_f32 v[126:127], v[126:127], v[160:161]
	v_pk_mul_f32 v[124:125], v[124:125], v[188:189]
	v_mov_b32_e32 v230, v64
	v_mov_b32_e32 v231, v65
	s_nop 1
	v_permlane32_swap_b32_e32 v224, v226
	v_permlane32_swap_b32_e32 v225, v227
	v_permlane32_swap_b32_e32 v228, v230
	v_permlane32_swap_b32_e32 v229, v231
	v_permlane16_swap_b32_e32 v224, v226
	v_permlane16_swap_b32_e32 v225, v227
	v_permlane16_swap_b32_e32 v228, v230
	v_permlane16_swap_b32_e32 v229, v231
	v_lshl_add_u64 v[240:241], v[78:79], 0, v[242:243]
	global_store_dwordx4 v[240:241], v[224:227], off nt
	global_store_dwordx4 v[240:241], v[228:231], off offset:256 nt
	v_add_u32_e32 v64, s78, v66
	v_cvt_pk_bf16_f32 v124, v124, v125
	v_cvt_pk_bf16_f32 v125, v126, v127
	v_ashrrev_i32_e32 v65, 31, v64
	v_mov_b32_e32 v196, v124
	v_mov_b32_e32 v197, v125
	s_nop 1
	v_permlane32_swap_b32_e32 v196, v198
	v_permlane32_swap_b32_e32 v197, v199
	v_permlane32_swap_b32_e32 v200, v202
	v_permlane32_swap_b32_e32 v201, v203
	v_permlane16_swap_b32_e32 v196, v198
	v_permlane16_swap_b32_e32 v197, v199
	v_permlane16_swap_b32_e32 v200, v202
	v_permlane16_swap_b32_e32 v201, v203
	v_lshl_add_u64 v[240:241], v[174:175], 0, v[242:243]
	global_store_dwordx4 v[240:241], v[196:199], off nt
	global_store_dwordx4 v[240:241], v[200:203], off offset:256 nt
	v_lshl_add_u64 v[64:65], v[64:65], 2, s[44:45]
	global_load_dword v98, v[64:65], off
	global_load_dwordx2 v[72:73], v[142:143], off nt
	global_load_dwordx2 v[74:75], v[142:143], off offset:512 nt
	global_load_dwordx2 v[76:77], v[142:143], off offset:1024 nt
	global_load_dwordx2 v[78:79], v[142:143], off offset:1536 nt
	v_add_u32_e32 v64, s53, v66
	v_ashrrev_i32_e32 v65, 31, v64
	v_lshl_add_u64 v[64:65], v[64:65], 2, s[44:45]
	global_load_dword v99, v[64:65], off
	global_load_dwordx2 v[80:81], v[142:143], off offset:2048 nt
	global_load_dwordx2 v[82:83], v[142:143], off offset:2560 nt
	global_load_dwordx2 v[84:85], v[142:143], off offset:3072 nt
	global_load_dwordx2 v[86:87], v[142:143], off offset:3584 nt
	v_add_u32_e32 v64, s60, v66
	v_ashrrev_i32_e32 v65, 31, v64
	v_lshl_add_u64 v[64:65], v[64:65], 2, s[44:45]
	v_add_co_u32_e32 v88, vcc, s68, v140
	s_waitcnt vmcnt(9)
	v_rcp_f32_e32 v98, v98
	v_addc_co_u32_e32 v89, vcc, 0, v141, vcc
	global_load_dword v102, v[64:65], off
	global_load_dwordx2 v[90:91], v[88:89], off nt
	v_add_u32_e32 v64, s61, v66
	v_ashrrev_i32_e32 v65, 31, v64
	v_lshl_add_u64 v[64:65], v[64:65], 2, s[44:45]
	global_load_dwordx2 v[92:93], v[88:89], off offset:512 nt
	global_load_dwordx2 v[94:95], v[88:89], off offset:1024 nt
	global_load_dwordx2 v[96:97], v[88:89], off offset:1536 nt
	global_load_dwordx2 v[70:71], v[88:89], off offset:2048 nt
	global_load_dword v103, v[64:65], off
	global_load_dwordx2 v[68:69], v[88:89], off offset:2560 nt
	global_load_dwordx2 v[66:67], v[88:89], off offset:3072 nt
	s_nop 0
	global_load_dwordx2 v[64:65], v[88:89], off offset:3584 nt
	v_add_u32_e32 v88, 0x80, v138
	v_ashrrev_i32_e32 v89, 31, v88
	s_waitcnt vmcnt(18)
	v_lshlrev_b32_e32 v100, 16, v72
	v_and_b32_e32 v101, 0xffff0000, v72
	v_lshlrev_b32_e32 v72, 16, v73
	v_and_b32_e32 v73, 0xffff0000, v73
	s_waitcnt vmcnt(14)
	v_pk_mul_f32 v[60:61], v[60:61], v[98:99] op_sel_hi:[1,0]
	v_pk_mul_f32 v[62:63], v[62:63], v[98:99] op_sel_hi:[1,0]
	v_lshlrev_b64 v[88:89], 11, v[88:89]
	v_pk_mul_f32 v[62:63], v[62:63], v[72:73]
	v_pk_mul_f32 v[60:61], v[60:61], v[100:101]
	v_lshlrev_b32_e32 v72, 16, v75
	v_cvt_pk_bf16_f32 v60, v60, v61
	v_cvt_pk_bf16_f32 v61, v62, v63
	v_lshl_add_u64 v[62:63], s[24:25], 0, v[88:89]
	v_lshl_add_u64 v[62:63], v[62:63], 0, s[28:29]
	v_lshl_add_u64 v[62:63], v[62:63], 0, s[6:7]
	v_lshl_add_u64 v[62:63], v[62:63], 0, v[136:137]
	v_mov_b32_e32 v232, v60
	v_mov_b32_e32 v233, v61
	v_lshlrev_b32_e32 v60, 16, v74
	v_and_b32_e32 v61, 0xffff0000, v74
	v_and_b32_e32 v73, 0xffff0000, v75
	v_pk_mul_f32 v[56:57], v[56:57], v[98:99] op_sel_hi:[1,0]
	v_pk_mul_f32 v[58:59], v[58:59], v[98:99] op_sel_hi:[1,0]
	v_pk_mul_f32 v[56:57], v[56:57], v[60:61]
	v_pk_mul_f32 v[58:59], v[58:59], v[72:73]
	v_cvt_pk_bf16_f32 v56, v56, v57
	v_cvt_pk_bf16_f32 v57, v58, v59
	v_mov_b32_e32 v234, v56
	v_mov_b32_e32 v235, v57
	v_lshlrev_b32_e32 v56, 16, v76
	v_and_b32_e32 v57, 0xffff0000, v76
	v_lshlrev_b32_e32 v58, 16, v77
	v_and_b32_e32 v59, 0xffff0000, v77
	v_pk_mul_f32 v[52:53], v[52:53], v[98:99] op_sel_hi:[1,0]
	v_pk_mul_f32 v[54:55], v[54:55], v[98:99] op_sel_hi:[1,0]
	v_pk_mul_f32 v[52:53], v[52:53], v[56:57]
	v_pk_mul_f32 v[54:55], v[54:55], v[58:59]
	v_cvt_pk_bf16_f32 v52, v52, v53
	v_cvt_pk_bf16_f32 v53, v54, v55
	v_mov_b32_e32 v236, v52
	v_mov_b32_e32 v237, v53
	v_lshlrev_b32_e32 v52, 16, v78
	v_and_b32_e32 v53, 0xffff0000, v78
	v_lshlrev_b32_e32 v54, 16, v79
	v_and_b32_e32 v55, 0xffff0000, v79
	v_pk_mul_f32 v[48:49], v[48:49], v[98:99] op_sel_hi:[1,0]
	v_pk_mul_f32 v[50:51], v[50:51], v[98:99] op_sel_hi:[1,0]
	v_pk_mul_f32 v[48:49], v[48:49], v[52:53]
	v_pk_mul_f32 v[50:51], v[50:51], v[54:55]
	v_cvt_pk_bf16_f32 v48, v48, v49
	v_cvt_pk_bf16_f32 v49, v50, v51
	v_rcp_f32_e32 v50, v99
	v_mov_b32_e32 v238, v48
	v_mov_b32_e32 v239, v49
	s_nop 1
	v_permlane32_swap_b32_e32 v232, v234
	v_permlane32_swap_b32_e32 v233, v235
	v_permlane32_swap_b32_e32 v236, v238
	v_permlane32_swap_b32_e32 v237, v239
	v_permlane16_swap_b32_e32 v232, v234
	v_permlane16_swap_b32_e32 v233, v235
	v_permlane16_swap_b32_e32 v236, v238
	v_permlane16_swap_b32_e32 v237, v239
	v_lshl_add_u64 v[240:241], v[62:63], 0, v[242:243]
	global_store_dwordx4 v[240:241], v[232:235], off nt
	global_store_dwordx4 v[240:241], v[236:239], off offset:256 nt
	v_add_u32_e32 v48, 0x90, v138
	v_ashrrev_i32_e32 v49, 31, v48
	s_waitcnt vmcnt(15)
; __device__ __forceinline__ u32x2 pk4(f32x4 v) { u32x2 r; r.x = pk_bf16(v[0], v[1]); r.y = pk_bf16(v[2], v[3]); return r; }
; __device__ __forceinline__ f32x4 unpk4(u32x2 v) { return (f32x4){bf_lo(v.x), bf_hi(v.x), bf_lo(v.y), bf_hi(v.y)}; }
;     __device__ __forceinline__ void operator()(const f32x4 (&acc)[2][2][4][2], const Unit& u, int wr, int wc, int fr_in, int fq_in) const {
;     ...
; #pragma unroll
;             for (int m = 0; m < 4; ++m) {
;                 const int row = u.pm * 256 + ai * 128 + wr * 64 + m * 16 + fr; const float inv = __builtin_amdgcn_rcpf(rs[m]);
; #pragma unroll
;                 for (int bj = 0; bj < 2; ++bj)
; #pragma unroll
;                     for (int n = 0; n < 2; ++n)
;                         *(u32x2*)(HX + (size_t)row * 1024 + u.pn * 256 + bj * 128 + wc * 32 + n * 16 + fq * 4) = pk4(unpk4(z[m][bj][n]) * (acc[ai][bj][m][n] * inv));
;             }
	v_lshlrev_b32_e32 v52, 16, v80
	v_and_b32_e32 v53, 0xffff0000, v80
	v_lshlrev_b32_e32 v54, 16, v81
	v_and_b32_e32 v55, 0xffff0000, v81
	v_pk_mul_f32 v[44:45], v[44:45], v[50:51] op_sel_hi:[1,0]
	v_pk_mul_f32 v[46:47], v[46:47], v[50:51] op_sel_hi:[1,0]
	v_lshlrev_b64 v[48:49], 11, v[48:49]
	v_pk_mul_f32 v[46:47], v[46:47], v[54:55]
	v_pk_mul_f32 v[44:45], v[44:45], v[52:53]
	v_pk_mul_f32 v[40:41], v[40:41], v[50:51] op_sel_hi:[1,0]
	v_cvt_pk_bf16_f32 v44, v44, v45
	v_cvt_pk_bf16_f32 v45, v46, v47
	v_lshl_add_u64 v[46:47], s[24:25], 0, v[48:49]
	v_lshl_add_u64 v[46:47], v[46:47], 0, s[28:29]
	v_lshl_add_u64 v[46:47], v[46:47], 0, s[6:7]
	v_lshl_add_u64 v[46:47], v[46:47], 0, v[136:137]
	v_mov_b32_e32 v204, v44
	v_mov_b32_e32 v205, v45
	s_waitcnt vmcnt(14)
	v_lshlrev_b32_e32 v44, 16, v82
	v_and_b32_e32 v45, 0xffff0000, v82
	v_lshlrev_b32_e32 v48, 16, v83
	v_and_b32_e32 v49, 0xffff0000, v83
	v_pk_mul_f32 v[42:43], v[42:43], v[50:51] op_sel_hi:[1,0]
	v_pk_mul_f32 v[40:41], v[40:41], v[44:45]
	v_pk_mul_f32 v[42:43], v[42:43], v[48:49]
	v_cvt_pk_bf16_f32 v40, v40, v41
	v_cvt_pk_bf16_f32 v41, v42, v43
	v_mov_b32_e32 v206, v40
	v_mov_b32_e32 v207, v41
	s_waitcnt vmcnt(13)
	v_lshlrev_b32_e32 v40, 16, v84
	v_and_b32_e32 v41, 0xffff0000, v84
	v_lshlrev_b32_e32 v42, 16, v85
	v_and_b32_e32 v43, 0xffff0000, v85
	v_pk_mul_f32 v[36:37], v[36:37], v[50:51] op_sel_hi:[1,0]
	v_pk_mul_f32 v[38:39], v[38:39], v[50:51] op_sel_hi:[1,0]
	v_pk_mul_f32 v[36:37], v[36:37], v[40:41]
	v_pk_mul_f32 v[38:39], v[38:39], v[42:43]
	v_cvt_pk_bf16_f32 v36, v36, v37
	v_cvt_pk_bf16_f32 v37, v38, v39
	v_mov_b32_e32 v208, v36
	v_mov_b32_e32 v209, v37
	s_waitcnt vmcnt(12)
	v_lshlrev_b32_e32 v36, 16, v86
	v_and_b32_e32 v37, 0xffff0000, v86
	v_lshlrev_b32_e32 v38, 16, v87
	v_and_b32_e32 v39, 0xffff0000, v87
	v_pk_mul_f32 v[32:33], v[32:33], v[50:51] op_sel_hi:[1,0]
	v_pk_mul_f32 v[34:35], v[34:35], v[50:51] op_sel_hi:[1,0]
	v_pk_mul_f32 v[32:33], v[32:33], v[36:37]
	v_pk_mul_f32 v[34:35], v[34:35], v[38:39]
	v_cvt_pk_bf16_f32 v32, v32, v33
	v_cvt_pk_bf16_f32 v33, v34, v35
	s_waitcnt vmcnt(11)
	v_rcp_f32_e32 v34, v102
	v_mov_b32_e32 v210, v32
	v_mov_b32_e32 v211, v33
	s_nop 1
	v_permlane32_swap_b32_e32 v204, v206
	v_permlane32_swap_b32_e32 v205, v207
	v_permlane32_swap_b32_e32 v208, v210
	v_permlane32_swap_b32_e32 v209, v211
	v_permlane16_swap_b32_e32 v204, v206
	v_permlane16_swap_b32_e32 v205, v207
	v_permlane16_swap_b32_e32 v208, v210
	v_permlane16_swap_b32_e32 v209, v211
	v_lshl_add_u64 v[240:241], v[46:47], 0, v[242:243]
	global_store_dwordx4 v[240:241], v[204:207], off nt
	global_store_dwordx4 v[240:241], v[208:211], off offset:256 nt
	v_add_u32_e32 v32, 0xa0, v138
	v_ashrrev_i32_e32 v33, 31, v32
	s_waitcnt vmcnt(12)
	v_lshlrev_b32_e32 v36, 16, v90
	v_and_b32_e32 v37, 0xffff0000, v90
	v_lshlrev_b32_e32 v38, 16, v91
	v_and_b32_e32 v39, 0xffff0000, v91
	v_pk_mul_f32 v[28:29], v[28:29], v[34:35] op_sel_hi:[1,0]
	v_pk_mul_f32 v[30:31], v[30:31], v[34:35] op_sel_hi:[1,0]
	v_lshlrev_b64 v[32:33], 11, v[32:33]
	v_pk_mul_f32 v[30:31], v[30:31], v[38:39]
	v_pk_mul_f32 v[28:29], v[28:29], v[36:37]
	v_pk_mul_f32 v[24:25], v[24:25], v[34:35] op_sel_hi:[1,0]
	v_cvt_pk_bf16_f32 v28, v28, v29
	v_cvt_pk_bf16_f32 v29, v30, v31
	v_lshl_add_u64 v[30:31], s[24:25], 0, v[32:33]
	v_lshl_add_u64 v[30:31], v[30:31], 0, s[28:29]
	v_lshl_add_u64 v[30:31], v[30:31], 0, s[6:7]
	v_lshl_add_u64 v[30:31], v[30:31], 0, v[136:137]
	v_mov_b32_e32 v212, v28
	v_mov_b32_e32 v213, v29
	s_waitcnt vmcnt(11)
	v_lshlrev_b32_e32 v28, 16, v92
	v_and_b32_e32 v29, 0xffff0000, v92
	v_lshlrev_b32_e32 v32, 16, v93
	v_and_b32_e32 v33, 0xffff0000, v93
	v_pk_mul_f32 v[26:27], v[26:27], v[34:35] op_sel_hi:[1,0]
	v_pk_mul_f32 v[24:25], v[24:25], v[28:29]
	v_pk_mul_f32 v[26:27], v[26:27], v[32:33]
	v_cvt_pk_bf16_f32 v24, v24, v25
	v_cvt_pk_bf16_f32 v25, v26, v27
	v_mov_b32_e32 v214, v24
	v_mov_b32_e32 v215, v25
	s_waitcnt vmcnt(10)
; __device__ __forceinline__ u32x2 pk4(f32x4 v) { u32x2 r; r.x = pk_bf16(v[0], v[1]); r.y = pk_bf16(v[2], v[3]); return r; }
; __device__ __forceinline__ f32x4 unpk4(u32x2 v) { return (f32x4){bf_lo(v.x), bf_hi(v.x), bf_lo(v.y), bf_hi(v.y)}; }
; #define GP_BAR __builtin_amdgcn_s_barrier()
; template <class Epi, class Sched>
; __device__ __forceinline__ void gemm_phase(LAS unsigned char* lds, const int lda, const int ldb, const int K, const Sched& S, const Epi& E, const int widx) {
;     ...
;         if (!has_next) break;
;         if (!epi_keeps(E, cur)) {
; #pragma unroll
;         for (int a = 0; a < 2; ++a)
; #pragma unroll
;             for (int b = 0; b < 2; ++b)
; #pragma unroll
;                 for (int m = 0; m < 4; ++m)
; #pragma unroll
;                     for (int n = 0; n < 2; ++n) acc[a][b][m][n] = (f32x4){0.f, 0.f, 0.f, 0.f};
;         }
;         cur = nxt; cA = nA; cB = nB; ++ui;
;         if (wr == 1) GP_BAR;
;     __device__ __forceinline__ void operator()(const f32x4 (&acc)[2][2][4][2], const Unit& u, int wr, int wc, int fr_in, int fq_in) const {
;     ...
; #pragma unroll
;             for (int m = 0; m < 4; ++m) {
;                 const int row = u.pm * 256 + ai * 128 + wr * 64 + m * 16 + fr; const float inv = __builtin_amdgcn_rcpf(rs[m]);
; #pragma unroll
;                 for (int bj = 0; bj < 2; ++bj)
; #pragma unroll
;                     for (int n = 0; n < 2; ++n)
;                         *(u32x2*)(HX + (size_t)row * 1024 + u.pn * 256 + bj * 128 + wc * 32 + n * 16 + fq * 4) = pk4(unpk4(z[m][bj][n]) * (acc[ai][bj][m][n] * inv));
;             }
	v_lshlrev_b32_e32 v24, 16, v94
	v_and_b32_e32 v25, 0xffff0000, v94
	v_lshlrev_b32_e32 v26, 16, v95
	v_and_b32_e32 v27, 0xffff0000, v95
	v_pk_mul_f32 v[20:21], v[20:21], v[34:35] op_sel_hi:[1,0]
	v_pk_mul_f32 v[22:23], v[22:23], v[34:35] op_sel_hi:[1,0]
	v_pk_mul_f32 v[20:21], v[20:21], v[24:25]
	v_pk_mul_f32 v[22:23], v[22:23], v[26:27]
	v_cvt_pk_bf16_f32 v20, v20, v21
	v_cvt_pk_bf16_f32 v21, v22, v23
	v_mov_b32_e32 v216, v20
	v_mov_b32_e32 v217, v21
	s_waitcnt vmcnt(9)
	v_lshlrev_b32_e32 v20, 16, v96
	v_and_b32_e32 v21, 0xffff0000, v96
	v_lshlrev_b32_e32 v22, 16, v97
	v_and_b32_e32 v23, 0xffff0000, v97
	v_pk_mul_f32 v[16:17], v[16:17], v[34:35] op_sel_hi:[1,0]
	v_pk_mul_f32 v[18:19], v[18:19], v[34:35] op_sel_hi:[1,0]
	v_pk_mul_f32 v[16:17], v[16:17], v[20:21]
	v_pk_mul_f32 v[18:19], v[18:19], v[22:23]
	v_cvt_pk_bf16_f32 v16, v16, v17
	v_cvt_pk_bf16_f32 v17, v18, v19
	s_waitcnt vmcnt(7)
	v_rcp_f32_e32 v18, v103
	v_mov_b32_e32 v218, v16
	v_mov_b32_e32 v219, v17
	s_nop 1
	v_permlane32_swap_b32_e32 v212, v214
	v_permlane32_swap_b32_e32 v213, v215
	v_permlane32_swap_b32_e32 v216, v218
	v_permlane32_swap_b32_e32 v217, v219
	v_permlane16_swap_b32_e32 v212, v214
	v_permlane16_swap_b32_e32 v213, v215
	v_permlane16_swap_b32_e32 v216, v218
	v_permlane16_swap_b32_e32 v217, v219
	v_lshl_add_u64 v[240:241], v[30:31], 0, v[242:243]
	global_store_dwordx4 v[240:241], v[212:215], off nt
	global_store_dwordx4 v[240:241], v[216:219], off offset:256 nt
	v_add_u32_e32 v16, 0xb0, v138
	v_ashrrev_i32_e32 v17, 31, v16
	v_lshlrev_b32_e32 v20, 16, v70
	v_and_b32_e32 v21, 0xffff0000, v70
	v_lshlrev_b32_e32 v22, 16, v71
	v_and_b32_e32 v23, 0xffff0000, v71
	v_pk_mul_f32 v[12:13], v[12:13], v[18:19] op_sel_hi:[1,0]
	v_pk_mul_f32 v[14:15], v[14:15], v[18:19] op_sel_hi:[1,0]
	v_lshlrev_b64 v[16:17], 11, v[16:17]
	v_pk_mul_f32 v[14:15], v[14:15], v[22:23]
	v_pk_mul_f32 v[12:13], v[12:13], v[20:21]
	v_pk_mul_f32 v[8:9], v[8:9], v[18:19] op_sel_hi:[1,0]
	v_cvt_pk_bf16_f32 v12, v12, v13
	v_cvt_pk_bf16_f32 v13, v14, v15
	v_lshl_add_u64 v[14:15], s[24:25], 0, v[16:17]
	v_lshl_add_u64 v[14:15], v[14:15], 0, s[28:29]
	v_lshl_add_u64 v[14:15], v[14:15], 0, s[6:7]
	v_lshl_add_u64 v[14:15], v[14:15], 0, v[136:137]
	v_mov_b32_e32 v224, v12
	v_mov_b32_e32 v225, v13
	s_waitcnt vmcnt(8)
	v_lshlrev_b32_e32 v12, 16, v68
	v_and_b32_e32 v13, 0xffff0000, v68
	v_lshlrev_b32_e32 v16, 16, v69
	v_and_b32_e32 v17, 0xffff0000, v69
	v_pk_mul_f32 v[10:11], v[10:11], v[18:19] op_sel_hi:[1,0]
	v_pk_mul_f32 v[8:9], v[8:9], v[12:13]
	v_pk_mul_f32 v[10:11], v[10:11], v[16:17]
	v_cvt_pk_bf16_f32 v8, v8, v9
	v_cvt_pk_bf16_f32 v9, v10, v11
	v_mov_b32_e32 v226, v8
	v_mov_b32_e32 v227, v9
	s_waitcnt vmcnt(7)
	v_lshlrev_b32_e32 v8, 16, v66
	v_and_b32_e32 v9, 0xffff0000, v66
	v_lshlrev_b32_e32 v10, 16, v67
	v_and_b32_e32 v11, 0xffff0000, v67
	v_pk_mul_f32 v[4:5], v[4:5], v[18:19] op_sel_hi:[1,0]
	v_pk_mul_f32 v[6:7], v[6:7], v[18:19] op_sel_hi:[1,0]
	v_pk_mul_f32 v[4:5], v[4:5], v[8:9]
	v_pk_mul_f32 v[6:7], v[6:7], v[10:11]
	v_cvt_pk_bf16_f32 v4, v4, v5
	v_cvt_pk_bf16_f32 v5, v6, v7
	v_mov_b32_e32 v228, v4
	v_mov_b32_e32 v229, v5
	s_waitcnt vmcnt(6)
	v_lshlrev_b32_e32 v4, 16, v64
	v_and_b32_e32 v5, 0xffff0000, v64
	v_lshlrev_b32_e32 v6, 16, v65
	v_and_b32_e32 v7, 0xffff0000, v65
	v_pk_mul_f32 v[0:1], v[0:1], v[18:19] op_sel_hi:[1,0]
	v_pk_mul_f32 v[2:3], v[2:3], v[18:19] op_sel_hi:[1,0]
	v_pk_mul_f32 v[0:1], v[0:1], v[4:5]
	v_pk_mul_f32 v[2:3], v[2:3], v[6:7]
	v_cvt_pk_bf16_f32 v0, v0, v1
	v_cvt_pk_bf16_f32 v1, v2, v3
	s_andn2_b64 vcc, exec, s[58:59]
	s_mov_b64 s[28:29], -1
	v_mov_b32_e32 v230, v0
	v_mov_b32_e32 v231, v1
	s_nop 1
	v_permlane32_swap_b32_e32 v224, v226
	v_permlane32_swap_b32_e32 v225, v227
	v_permlane32_swap_b32_e32 v228, v230
	v_permlane32_swap_b32_e32 v229, v231
	v_permlane16_swap_b32_e32 v224, v226
	v_permlane16_swap_b32_e32 v225, v227
	v_permlane16_swap_b32_e32 v228, v230
	v_permlane16_swap_b32_e32 v229, v231
	v_lshl_add_u64 v[240:241], v[14:15], 0, v[242:243]
	global_store_dwordx4 v[240:241], v[224:227], off nt
	global_store_dwordx4 v[240:241], v[228:231], off offset:256 nt
	s_cbranch_vccnz .LBB0_463
	s_andn2_b64 vcc, exec, s[8:9]
	s_cbranch_vccnz .LBB0_462
	s_barrier
	s_branch .LBB0_462
